# phase-0 rownorm loop software-pipelined: 4 row loads issued together, 2 items prefetched ahead in 3 register sets, counted vmcnt waits (on top of v_prio)
# speedup vs baseline: 1.0026x; 1.0026x over previous
.LBB0_146:
	s_or_b64 exec, exec, s[4:5]
	s_cmpk_lt_i32 s2, 0x2000
	s_cselect_b64 s[6:7], -1, 0
	s_cmpk_gt_i32 s2, 0x1fff
	v_mbcnt_lo_u32_b32 v221, -1, 0
	s_cbranch_scc1 .LBB0_151
	s_add_u32 s0, s72, 0x3000000
	s_addc_u32 s1, s73, 0
	s_add_u32 s4, s72, 0x7000000
	s_addc_u32 s5, s73, 0
	v_readlane_b32 s16, v254, 6
	v_readlane_b32 s17, v254, 7
	v_mbcnt_hi_u32_b32 v4, -1, v221
	v_and_b32_e32 v4, 63, v4
	v_lshrrev_b32_e32 v5, 6, v220
	v_xor_b32_e32 v6, 32, v4
	v_lshlrev_b32_e32 v6, 2, v6
	v_xor_b32_e32 v7, 16, v4
	v_lshlrev_b32_e32 v7, 2, v7
	v_xor_b32_e32 v8, 8, v4
	v_lshlrev_b32_e32 v8, 2, v8
	v_xor_b32_e32 v9, 4, v4
	v_lshlrev_b32_e32 v9, 2, v9
	v_xor_b32_e32 v10, 2, v4
	v_lshlrev_b32_e32 v10, 2, v10
	v_xor_b32_e32 v11, 1, v4
	v_lshlrev_b32_e32 v11, 2, v11
	v_mov_b32_e32 v1, 0
	v_mov_b32_e32 v3, 0
	v_mov_b32_e32 v12, 0x358637bd
	v_mov_b32_e32 v13, 1
	v_lshlrev_b32_e32 v80, 4, v4
	v_lshlrev_b32_e32 v81, 3, v4
	v_mov_b32_e32 v67, 0
	v_mov_b32_e32 v73, 0
	v_mov_b32_e32 v79, 0
	s_movk_i32 s13, 0x7fff
	s_mov_b32 s14, 0x800000
	s_mov_b32 s12, s74
	s_mov_b32 s15, s2
	s_min_u32 s3, s15, 0x1fff
	s_lshl_b32 s3, s3, 2
	v_add_u32_e32 v66, s3, v5
	v_lshl_add_u32 v2, v66, 12, v80
	v_lshl_add_u64 v[62:63], s[16:17], 0, v[2:3]
	v_lshl_add_u32 v2, v66, 11, v81
	v_lshl_add_u64 v[64:65], s[0:1], 0, v[2:3]
	global_load_dwordx4 v[14:17], v[62:63], off
	global_load_dwordx4 v[18:21], v[62:63], off offset:1024
	global_load_dwordx4 v[22:25], v[62:63], off offset:2048
	global_load_dwordx4 v[26:29], v[62:63], off offset:3072
	s_mov_b32 s3, s12
	s_add_i32 s3, s3, s15
	s_min_u32 s3, s3, 0x1fff
	s_lshl_b32 s3, s3, 2
	v_add_u32_e32 v72, s3, v5
	v_lshl_add_u32 v2, v72, 12, v80
	v_lshl_add_u64 v[68:69], s[16:17], 0, v[2:3]
	v_lshl_add_u32 v2, v72, 11, v81
	v_lshl_add_u64 v[70:71], s[0:1], 0, v[2:3]
	global_load_dwordx4 v[30:33], v[68:69], off
	global_load_dwordx4 v[34:37], v[68:69], off offset:1024
	global_load_dwordx4 v[38:41], v[68:69], off offset:2048
	global_load_dwordx4 v[42:45], v[68:69], off offset:3072
	s_mul_i32 s3, s12, 2
	s_add_i32 s3, s3, s15
	s_min_u32 s3, s3, 0x1fff
	s_lshl_b32 s3, s3, 2
	v_add_u32_e32 v78, s3, v5
	v_lshl_add_u32 v2, v78, 12, v80
	v_lshl_add_u64 v[74:75], s[16:17], 0, v[2:3]
	v_lshl_add_u32 v2, v78, 11, v81
	v_lshl_add_u64 v[76:77], s[0:1], 0, v[2:3]
	global_load_dwordx4 v[46:49], v[74:75], off
	global_load_dwordx4 v[50:53], v[74:75], off offset:1024
	global_load_dwordx4 v[54:57], v[74:75], off offset:2048
	global_load_dwordx4 v[58:61], v[74:75], off offset:3072
	s_waitcnt vmcnt(11)
	v_and_b32_sdwa v85, v17, v13 dst_sel:DWORD dst_unused:UNUSED_PAD src0_sel:WORD_1 src1_sel:DWORD
	v_and_b32_sdwa v83, v15, v13 dst_sel:DWORD dst_unused:UNUSED_PAD src0_sel:WORD_1 src1_sel:DWORD
	v_and_b32_sdwa v84, v16, v13 dst_sel:DWORD dst_unused:UNUSED_PAD src0_sel:WORD_1 src1_sel:DWORD
	v_and_b32_sdwa v82, v14, v13 dst_sel:DWORD dst_unused:UNUSED_PAD src0_sel:WORD_1 src1_sel:DWORD
	v_add3_u32 v85, v17, v85, s13
	v_add3_u32 v83, v15, v83, s13
	v_add3_u32 v82, v14, v82, s13
	v_add3_u32 v84, v16, v84, s13
	v_and_b32_e32 v85, 0xffff0000, v85
	v_and_b32_e32 v83, 0xffff0000, v83
	v_or_b32_sdwa v87, v85, v84 dst_sel:DWORD dst_unused:UNUSED_PAD src0_sel:DWORD src1_sel:WORD_1
	v_or_b32_sdwa v86, v83, v82 dst_sel:DWORD dst_unused:UNUSED_PAD src0_sel:DWORD src1_sel:WORD_1
	global_store_dwordx2 v[64:65], v[86:87], off
	v_mul_f32_e32 v95, v15, v15
	v_fmac_f32_e32 v95, v14, v14
	v_fmac_f32_e32 v95, v16, v16
	v_fmac_f32_e32 v95, v17, v17
	s_waitcnt vmcnt(11)
	v_and_b32_sdwa v85, v21, v13 dst_sel:DWORD dst_unused:UNUSED_PAD src0_sel:WORD_1 src1_sel:DWORD
	v_and_b32_sdwa v83, v19, v13 dst_sel:DWORD dst_unused:UNUSED_PAD src0_sel:WORD_1 src1_sel:DWORD
	v_and_b32_sdwa v84, v20, v13 dst_sel:DWORD dst_unused:UNUSED_PAD src0_sel:WORD_1 src1_sel:DWORD
	v_and_b32_sdwa v82, v18, v13 dst_sel:DWORD dst_unused:UNUSED_PAD src0_sel:WORD_1 src1_sel:DWORD
	v_add3_u32 v85, v21, v85, s13
	v_add3_u32 v83, v19, v83, s13
	v_add3_u32 v82, v18, v82, s13
	v_add3_u32 v84, v20, v84, s13
	v_and_b32_e32 v85, 0xffff0000, v85
	v_and_b32_e32 v83, 0xffff0000, v83
	v_or_b32_sdwa v89, v85, v84 dst_sel:DWORD dst_unused:UNUSED_PAD src0_sel:DWORD src1_sel:WORD_1
	v_or_b32_sdwa v88, v83, v82 dst_sel:DWORD dst_unused:UNUSED_PAD src0_sel:DWORD src1_sel:WORD_1
	global_store_dwordx2 v[64:65], v[88:89], off offset:512
	v_mul_f32_e32 v94, v19, v19
	v_fmac_f32_e32 v94, v18, v18
	v_fmac_f32_e32 v94, v20, v20
	v_fmac_f32_e32 v94, v21, v21
	v_add_f32_e32 v95, v95, v94
	s_waitcnt vmcnt(11)
	v_and_b32_sdwa v85, v25, v13 dst_sel:DWORD dst_unused:UNUSED_PAD src0_sel:WORD_1 src1_sel:DWORD
	v_and_b32_sdwa v83, v23, v13 dst_sel:DWORD dst_unused:UNUSED_PAD src0_sel:WORD_1 src1_sel:DWORD
	v_and_b32_sdwa v84, v24, v13 dst_sel:DWORD dst_unused:UNUSED_PAD src0_sel:WORD_1 src1_sel:DWORD
	v_and_b32_sdwa v82, v22, v13 dst_sel:DWORD dst_unused:UNUSED_PAD src0_sel:WORD_1 src1_sel:DWORD
	v_add3_u32 v85, v25, v85, s13
	v_add3_u32 v83, v23, v83, s13
	v_add3_u32 v82, v22, v82, s13
	v_add3_u32 v84, v24, v84, s13
	v_and_b32_e32 v85, 0xffff0000, v85
	v_and_b32_e32 v83, 0xffff0000, v83
	v_or_b32_sdwa v91, v85, v84 dst_sel:DWORD dst_unused:UNUSED_PAD src0_sel:DWORD src1_sel:WORD_1
	v_or_b32_sdwa v90, v83, v82 dst_sel:DWORD dst_unused:UNUSED_PAD src0_sel:DWORD src1_sel:WORD_1
	global_store_dwordx2 v[64:65], v[90:91], off offset:1024
	v_mul_f32_e32 v94, v23, v23
	v_fmac_f32_e32 v94, v22, v22
	v_fmac_f32_e32 v94, v24, v24
	v_fmac_f32_e32 v94, v25, v25
	v_add_f32_e32 v95, v95, v94
	s_waitcnt vmcnt(11)
	v_and_b32_sdwa v85, v29, v13 dst_sel:DWORD dst_unused:UNUSED_PAD src0_sel:WORD_1 src1_sel:DWORD
	v_and_b32_sdwa v83, v27, v13 dst_sel:DWORD dst_unused:UNUSED_PAD src0_sel:WORD_1 src1_sel:DWORD
	v_and_b32_sdwa v84, v28, v13 dst_sel:DWORD dst_unused:UNUSED_PAD src0_sel:WORD_1 src1_sel:DWORD
	v_and_b32_sdwa v82, v26, v13 dst_sel:DWORD dst_unused:UNUSED_PAD src0_sel:WORD_1 src1_sel:DWORD
	v_add3_u32 v85, v29, v85, s13
	v_add3_u32 v83, v27, v83, s13
	v_add3_u32 v82, v26, v82, s13
	v_add3_u32 v84, v28, v84, s13
	v_and_b32_e32 v85, 0xffff0000, v85
	v_and_b32_e32 v83, 0xffff0000, v83
	v_or_b32_sdwa v93, v85, v84 dst_sel:DWORD dst_unused:UNUSED_PAD src0_sel:DWORD src1_sel:WORD_1
	v_or_b32_sdwa v92, v83, v82 dst_sel:DWORD dst_unused:UNUSED_PAD src0_sel:DWORD src1_sel:WORD_1
	global_store_dwordx2 v[64:65], v[92:93], off offset:1536
	v_mul_f32_e32 v94, v27, v27
	v_fmac_f32_e32 v94, v26, v26
	v_fmac_f32_e32 v94, v28, v28
	v_fmac_f32_e32 v94, v29, v29
	v_add_f32_e32 v95, v95, v94
	ds_bpermute_b32 v94, v6, v95
	s_waitcnt lgkmcnt(0)
	v_add_f32_e32 v95, v95, v94
	ds_bpermute_b32 v94, v7, v95
	s_waitcnt lgkmcnt(0)
	v_add_f32_e32 v95, v95, v94
	ds_bpermute_b32 v94, v8, v95
	s_waitcnt lgkmcnt(0)
	v_add_f32_e32 v95, v95, v94
	ds_bpermute_b32 v94, v9, v95
	s_waitcnt lgkmcnt(0)
	v_add_f32_e32 v95, v95, v94
	ds_bpermute_b32 v94, v10, v95
	s_waitcnt lgkmcnt(0)
	v_add_f32_e32 v95, v95, v94
	ds_bpermute_b32 v94, v11, v95
	s_waitcnt lgkmcnt(0)
	v_add_f32_e32 v95, v95, v94
	v_cmp_eq_u32_e32 vcc, 0, v4
	s_and_saveexec_b64 s[8:9], vcc
	v_fmamk_f32 v95, v95, 0x3a800000, v12
	v_mul_f32_e32 v94, 0x4b800000, v95
	v_cmp_gt_f32_e32 vcc, s14, v95
	v_lshl_add_u64 v[82:83], v[66:67], 2, s[4:5]
	s_nop 0
	v_cndmask_b32_e32 v95, v95, v94, vcc
	v_rsq_f32_e32 v95, v95
	s_nop 0
	v_mul_f32_e32 v94, 0x45800000, v95
	v_cndmask_b32_e32 v95, v95, v94, vcc
	global_store_dword v[82:83], v95, off
	s_or_b64 exec, exec, s[8:9]
	s_add_i32 s15, s15, s12
	s_cmpk_lt_i32 s15, 0x2000
	s_cbranch_scc0 .Lrn_exit
	s_mul_i32 s3, s12, 2
	s_add_i32 s3, s3, s15
	s_min_u32 s3, s3, 0x1fff
	s_lshl_b32 s3, s3, 2
	v_add_u32_e32 v66, s3, v5
	v_lshl_add_u32 v2, v66, 12, v80
	v_lshl_add_u64 v[62:63], s[16:17], 0, v[2:3]
	v_lshl_add_u32 v2, v66, 11, v81
	v_lshl_add_u64 v[64:65], s[0:1], 0, v[2:3]
	global_load_dwordx4 v[14:17], v[62:63], off
	global_load_dwordx4 v[18:21], v[62:63], off offset:1024
	global_load_dwordx4 v[22:25], v[62:63], off offset:2048
	global_load_dwordx4 v[26:29], v[62:63], off offset:3072
	s_waitcnt vmcnt(16)
	v_and_b32_sdwa v85, v33, v13 dst_sel:DWORD dst_unused:UNUSED_PAD src0_sel:WORD_1 src1_sel:DWORD
	v_and_b32_sdwa v83, v31, v13 dst_sel:DWORD dst_unused:UNUSED_PAD src0_sel:WORD_1 src1_sel:DWORD
	v_and_b32_sdwa v84, v32, v13 dst_sel:DWORD dst_unused:UNUSED_PAD src0_sel:WORD_1 src1_sel:DWORD
	v_and_b32_sdwa v82, v30, v13 dst_sel:DWORD dst_unused:UNUSED_PAD src0_sel:WORD_1 src1_sel:DWORD
	v_add3_u32 v85, v33, v85, s13
	v_add3_u32 v83, v31, v83, s13
	v_add3_u32 v82, v30, v82, s13
	v_add3_u32 v84, v32, v84, s13
	v_and_b32_e32 v85, 0xffff0000, v85
	v_and_b32_e32 v83, 0xffff0000, v83
	v_or_b32_sdwa v87, v85, v84 dst_sel:DWORD dst_unused:UNUSED_PAD src0_sel:DWORD src1_sel:WORD_1
	v_or_b32_sdwa v86, v83, v82 dst_sel:DWORD dst_unused:UNUSED_PAD src0_sel:DWORD src1_sel:WORD_1
	global_store_dwordx2 v[70:71], v[86:87], off
	v_mul_f32_e32 v95, v31, v31
	v_fmac_f32_e32 v95, v30, v30
	v_fmac_f32_e32 v95, v32, v32
	v_fmac_f32_e32 v95, v33, v33
	s_waitcnt vmcnt(16)
	v_and_b32_sdwa v85, v37, v13 dst_sel:DWORD dst_unused:UNUSED_PAD src0_sel:WORD_1 src1_sel:DWORD
	v_and_b32_sdwa v83, v35, v13 dst_sel:DWORD dst_unused:UNUSED_PAD src0_sel:WORD_1 src1_sel:DWORD
	v_and_b32_sdwa v84, v36, v13 dst_sel:DWORD dst_unused:UNUSED_PAD src0_sel:WORD_1 src1_sel:DWORD
	v_and_b32_sdwa v82, v34, v13 dst_sel:DWORD dst_unused:UNUSED_PAD src0_sel:WORD_1 src1_sel:DWORD
	v_add3_u32 v85, v37, v85, s13
	v_add3_u32 v83, v35, v83, s13
	v_add3_u32 v82, v34, v82, s13
	v_add3_u32 v84, v36, v84, s13
	v_and_b32_e32 v85, 0xffff0000, v85
	v_and_b32_e32 v83, 0xffff0000, v83
	v_or_b32_sdwa v89, v85, v84 dst_sel:DWORD dst_unused:UNUSED_PAD src0_sel:DWORD src1_sel:WORD_1
	v_or_b32_sdwa v88, v83, v82 dst_sel:DWORD dst_unused:UNUSED_PAD src0_sel:DWORD src1_sel:WORD_1
	global_store_dwordx2 v[70:71], v[88:89], off offset:512
	v_mul_f32_e32 v94, v35, v35
	v_fmac_f32_e32 v94, v34, v34
	v_fmac_f32_e32 v94, v36, v36
	v_fmac_f32_e32 v94, v37, v37
	v_add_f32_e32 v95, v95, v94
	s_waitcnt vmcnt(16)
	v_and_b32_sdwa v85, v41, v13 dst_sel:DWORD dst_unused:UNUSED_PAD src0_sel:WORD_1 src1_sel:DWORD
	v_and_b32_sdwa v83, v39, v13 dst_sel:DWORD dst_unused:UNUSED_PAD src0_sel:WORD_1 src1_sel:DWORD
	v_and_b32_sdwa v84, v40, v13 dst_sel:DWORD dst_unused:UNUSED_PAD src0_sel:WORD_1 src1_sel:DWORD
	v_and_b32_sdwa v82, v38, v13 dst_sel:DWORD dst_unused:UNUSED_PAD src0_sel:WORD_1 src1_sel:DWORD
	v_add3_u32 v85, v41, v85, s13
	v_add3_u32 v83, v39, v83, s13
	v_add3_u32 v82, v38, v82, s13
	v_add3_u32 v84, v40, v84, s13
	v_and_b32_e32 v85, 0xffff0000, v85
	v_and_b32_e32 v83, 0xffff0000, v83
	v_or_b32_sdwa v91, v85, v84 dst_sel:DWORD dst_unused:UNUSED_PAD src0_sel:DWORD src1_sel:WORD_1
	v_or_b32_sdwa v90, v83, v82 dst_sel:DWORD dst_unused:UNUSED_PAD src0_sel:DWORD src1_sel:WORD_1
	global_store_dwordx2 v[70:71], v[90:91], off offset:1024
	v_mul_f32_e32 v94, v39, v39
	v_fmac_f32_e32 v94, v38, v38
	v_fmac_f32_e32 v94, v40, v40
	v_fmac_f32_e32 v94, v41, v41
	v_add_f32_e32 v95, v95, v94
	s_waitcnt vmcnt(16)
	v_and_b32_sdwa v85, v45, v13 dst_sel:DWORD dst_unused:UNUSED_PAD src0_sel:WORD_1 src1_sel:DWORD
	v_and_b32_sdwa v83, v43, v13 dst_sel:DWORD dst_unused:UNUSED_PAD src0_sel:WORD_1 src1_sel:DWORD
	v_and_b32_sdwa v84, v44, v13 dst_sel:DWORD dst_unused:UNUSED_PAD src0_sel:WORD_1 src1_sel:DWORD
	v_and_b32_sdwa v82, v42, v13 dst_sel:DWORD dst_unused:UNUSED_PAD src0_sel:WORD_1 src1_sel:DWORD
	v_add3_u32 v85, v45, v85, s13
	v_add3_u32 v83, v43, v83, s13
	v_add3_u32 v82, v42, v82, s13
	v_add3_u32 v84, v44, v84, s13
	v_and_b32_e32 v85, 0xffff0000, v85
	v_and_b32_e32 v83, 0xffff0000, v83
	v_or_b32_sdwa v93, v85, v84 dst_sel:DWORD dst_unused:UNUSED_PAD src0_sel:DWORD src1_sel:WORD_1
	v_or_b32_sdwa v92, v83, v82 dst_sel:DWORD dst_unused:UNUSED_PAD src0_sel:DWORD src1_sel:WORD_1
	global_store_dwordx2 v[70:71], v[92:93], off offset:1536
	v_mul_f32_e32 v94, v43, v43
	v_fmac_f32_e32 v94, v42, v42
	v_fmac_f32_e32 v94, v44, v44
	v_fmac_f32_e32 v94, v45, v45
	v_add_f32_e32 v95, v95, v94
	ds_bpermute_b32 v94, v6, v95
	s_waitcnt lgkmcnt(0)
	v_add_f32_e32 v95, v95, v94
	ds_bpermute_b32 v94, v7, v95
	s_waitcnt lgkmcnt(0)
	v_add_f32_e32 v95, v95, v94
	ds_bpermute_b32 v94, v8, v95
	s_waitcnt lgkmcnt(0)
	v_add_f32_e32 v95, v95, v94
	ds_bpermute_b32 v94, v9, v95
	s_waitcnt lgkmcnt(0)
	v_add_f32_e32 v95, v95, v94
	ds_bpermute_b32 v94, v10, v95
	s_waitcnt lgkmcnt(0)
	v_add_f32_e32 v95, v95, v94
	ds_bpermute_b32 v94, v11, v95
	s_waitcnt lgkmcnt(0)
	v_add_f32_e32 v95, v95, v94
	v_cmp_eq_u32_e32 vcc, 0, v4
	s_and_saveexec_b64 s[8:9], vcc
	v_fmamk_f32 v95, v95, 0x3a800000, v12
	v_mul_f32_e32 v94, 0x4b800000, v95
	v_cmp_gt_f32_e32 vcc, s14, v95
	v_lshl_add_u64 v[82:83], v[72:73], 2, s[4:5]
	s_nop 0
	v_cndmask_b32_e32 v95, v95, v94, vcc
	v_rsq_f32_e32 v95, v95
	s_nop 0
	v_mul_f32_e32 v94, 0x45800000, v95
	v_cndmask_b32_e32 v95, v95, v94, vcc
	global_store_dword v[82:83], v95, off
	s_or_b64 exec, exec, s[8:9]
	s_add_i32 s15, s15, s12
	s_cmpk_lt_i32 s15, 0x2000
	s_cbranch_scc0 .Lrn_exit
	s_mul_i32 s3, s12, 2
	s_add_i32 s3, s3, s15
	s_min_u32 s3, s3, 0x1fff
	s_lshl_b32 s3, s3, 2
	v_add_u32_e32 v72, s3, v5
	v_lshl_add_u32 v2, v72, 12, v80
	v_lshl_add_u64 v[68:69], s[16:17], 0, v[2:3]
	v_lshl_add_u32 v2, v72, 11, v81
	v_lshl_add_u64 v[70:71], s[0:1], 0, v[2:3]
	global_load_dwordx4 v[30:33], v[68:69], off
	global_load_dwordx4 v[34:37], v[68:69], off offset:1024
	global_load_dwordx4 v[38:41], v[68:69], off offset:2048
	global_load_dwordx4 v[42:45], v[68:69], off offset:3072
	s_waitcnt vmcnt(21)
	v_and_b32_sdwa v85, v49, v13 dst_sel:DWORD dst_unused:UNUSED_PAD src0_sel:WORD_1 src1_sel:DWORD
	v_and_b32_sdwa v83, v47, v13 dst_sel:DWORD dst_unused:UNUSED_PAD src0_sel:WORD_1 src1_sel:DWORD
	v_and_b32_sdwa v84, v48, v13 dst_sel:DWORD dst_unused:UNUSED_PAD src0_sel:WORD_1 src1_sel:DWORD
	v_and_b32_sdwa v82, v46, v13 dst_sel:DWORD dst_unused:UNUSED_PAD src0_sel:WORD_1 src1_sel:DWORD
	v_add3_u32 v85, v49, v85, s13
	v_add3_u32 v83, v47, v83, s13
	v_add3_u32 v82, v46, v82, s13
	v_add3_u32 v84, v48, v84, s13
	v_and_b32_e32 v85, 0xffff0000, v85
	v_and_b32_e32 v83, 0xffff0000, v83
	v_or_b32_sdwa v87, v85, v84 dst_sel:DWORD dst_unused:UNUSED_PAD src0_sel:DWORD src1_sel:WORD_1
	v_or_b32_sdwa v86, v83, v82 dst_sel:DWORD dst_unused:UNUSED_PAD src0_sel:DWORD src1_sel:WORD_1
	global_store_dwordx2 v[76:77], v[86:87], off
	v_mul_f32_e32 v95, v47, v47
	v_fmac_f32_e32 v95, v46, v46
	v_fmac_f32_e32 v95, v48, v48
	v_fmac_f32_e32 v95, v49, v49
	s_waitcnt vmcnt(21)
	v_and_b32_sdwa v85, v53, v13 dst_sel:DWORD dst_unused:UNUSED_PAD src0_sel:WORD_1 src1_sel:DWORD
	v_and_b32_sdwa v83, v51, v13 dst_sel:DWORD dst_unused:UNUSED_PAD src0_sel:WORD_1 src1_sel:DWORD
	v_and_b32_sdwa v84, v52, v13 dst_sel:DWORD dst_unused:UNUSED_PAD src0_sel:WORD_1 src1_sel:DWORD
	v_and_b32_sdwa v82, v50, v13 dst_sel:DWORD dst_unused:UNUSED_PAD src0_sel:WORD_1 src1_sel:DWORD
	v_add3_u32 v85, v53, v85, s13
	v_add3_u32 v83, v51, v83, s13
	v_add3_u32 v82, v50, v82, s13
	v_add3_u32 v84, v52, v84, s13
	v_and_b32_e32 v85, 0xffff0000, v85
	v_and_b32_e32 v83, 0xffff0000, v83
	v_or_b32_sdwa v89, v85, v84 dst_sel:DWORD dst_unused:UNUSED_PAD src0_sel:DWORD src1_sel:WORD_1
	v_or_b32_sdwa v88, v83, v82 dst_sel:DWORD dst_unused:UNUSED_PAD src0_sel:DWORD src1_sel:WORD_1
	global_store_dwordx2 v[76:77], v[88:89], off offset:512
	v_mul_f32_e32 v94, v51, v51
	v_fmac_f32_e32 v94, v50, v50
	v_fmac_f32_e32 v94, v52, v52
	v_fmac_f32_e32 v94, v53, v53
	v_add_f32_e32 v95, v95, v94
	s_waitcnt vmcnt(21)
	v_and_b32_sdwa v85, v57, v13 dst_sel:DWORD dst_unused:UNUSED_PAD src0_sel:WORD_1 src1_sel:DWORD
	v_and_b32_sdwa v83, v55, v13 dst_sel:DWORD dst_unused:UNUSED_PAD src0_sel:WORD_1 src1_sel:DWORD
	v_and_b32_sdwa v84, v56, v13 dst_sel:DWORD dst_unused:UNUSED_PAD src0_sel:WORD_1 src1_sel:DWORD
	v_and_b32_sdwa v82, v54, v13 dst_sel:DWORD dst_unused:UNUSED_PAD src0_sel:WORD_1 src1_sel:DWORD
	v_add3_u32 v85, v57, v85, s13
	v_add3_u32 v83, v55, v83, s13
	v_add3_u32 v82, v54, v82, s13
	v_add3_u32 v84, v56, v84, s13
	v_and_b32_e32 v85, 0xffff0000, v85
	v_and_b32_e32 v83, 0xffff0000, v83
	v_or_b32_sdwa v91, v85, v84 dst_sel:DWORD dst_unused:UNUSED_PAD src0_sel:DWORD src1_sel:WORD_1
	v_or_b32_sdwa v90, v83, v82 dst_sel:DWORD dst_unused:UNUSED_PAD src0_sel:DWORD src1_sel:WORD_1
	global_store_dwordx2 v[76:77], v[90:91], off offset:1024
	v_mul_f32_e32 v94, v55, v55
	v_fmac_f32_e32 v94, v54, v54
	v_fmac_f32_e32 v94, v56, v56
	v_fmac_f32_e32 v94, v57, v57
	v_add_f32_e32 v95, v95, v94
	s_waitcnt vmcnt(21)
	v_and_b32_sdwa v85, v61, v13 dst_sel:DWORD dst_unused:UNUSED_PAD src0_sel:WORD_1 src1_sel:DWORD
	v_and_b32_sdwa v83, v59, v13 dst_sel:DWORD dst_unused:UNUSED_PAD src0_sel:WORD_1 src1_sel:DWORD
	v_and_b32_sdwa v84, v60, v13 dst_sel:DWORD dst_unused:UNUSED_PAD src0_sel:WORD_1 src1_sel:DWORD
	v_and_b32_sdwa v82, v58, v13 dst_sel:DWORD dst_unused:UNUSED_PAD src0_sel:WORD_1 src1_sel:DWORD
	v_add3_u32 v85, v61, v85, s13
	v_add3_u32 v83, v59, v83, s13
	v_add3_u32 v82, v58, v82, s13
	v_add3_u32 v84, v60, v84, s13
	v_and_b32_e32 v85, 0xffff0000, v85
	v_and_b32_e32 v83, 0xffff0000, v83
	v_or_b32_sdwa v93, v85, v84 dst_sel:DWORD dst_unused:UNUSED_PAD src0_sel:DWORD src1_sel:WORD_1
	v_or_b32_sdwa v92, v83, v82 dst_sel:DWORD dst_unused:UNUSED_PAD src0_sel:DWORD src1_sel:WORD_1
	global_store_dwordx2 v[76:77], v[92:93], off offset:1536
	v_mul_f32_e32 v94, v59, v59
	v_fmac_f32_e32 v94, v58, v58
	v_fmac_f32_e32 v94, v60, v60
	v_fmac_f32_e32 v94, v61, v61
	v_add_f32_e32 v95, v95, v94
	ds_bpermute_b32 v94, v6, v95
	s_waitcnt lgkmcnt(0)
	v_add_f32_e32 v95, v95, v94
	ds_bpermute_b32 v94, v7, v95
	s_waitcnt lgkmcnt(0)
	v_add_f32_e32 v95, v95, v94
	ds_bpermute_b32 v94, v8, v95
	s_waitcnt lgkmcnt(0)
	v_add_f32_e32 v95, v95, v94
	ds_bpermute_b32 v94, v9, v95
	s_waitcnt lgkmcnt(0)
	v_add_f32_e32 v95, v95, v94
	ds_bpermute_b32 v94, v10, v95
	s_waitcnt lgkmcnt(0)
	v_add_f32_e32 v95, v95, v94
	ds_bpermute_b32 v94, v11, v95
	s_waitcnt lgkmcnt(0)
	v_add_f32_e32 v95, v95, v94
	v_cmp_eq_u32_e32 vcc, 0, v4
	s_and_saveexec_b64 s[8:9], vcc
	v_fmamk_f32 v95, v95, 0x3a800000, v12
	v_mul_f32_e32 v94, 0x4b800000, v95
	v_cmp_gt_f32_e32 vcc, s14, v95
	v_lshl_add_u64 v[82:83], v[78:79], 2, s[4:5]
	s_nop 0
	v_cndmask_b32_e32 v95, v95, v94, vcc
	v_rsq_f32_e32 v95, v95
	s_nop 0
	v_mul_f32_e32 v94, 0x45800000, v95
	v_cndmask_b32_e32 v95, v95, v94, vcc
	global_store_dword v[82:83], v95, off
	s_or_b64 exec, exec, s[8:9]
	s_add_i32 s15, s15, s12
	s_cmpk_lt_i32 s15, 0x2000
	s_cbranch_scc0 .Lrn_exit
.Lrn_loop:
	s_mul_i32 s3, s12, 2
	s_add_i32 s3, s3, s15
	s_min_u32 s3, s3, 0x1fff
	s_lshl_b32 s3, s3, 2
	v_add_u32_e32 v78, s3, v5
	v_lshl_add_u32 v2, v78, 12, v80
	v_lshl_add_u64 v[74:75], s[16:17], 0, v[2:3]
	v_lshl_add_u32 v2, v78, 11, v81
	v_lshl_add_u64 v[76:77], s[0:1], 0, v[2:3]
	global_load_dwordx4 v[46:49], v[74:75], off
	global_load_dwordx4 v[50:53], v[74:75], off offset:1024
	global_load_dwordx4 v[54:57], v[74:75], off offset:2048
	global_load_dwordx4 v[58:61], v[74:75], off offset:3072
	s_waitcnt vmcnt(21)
	v_and_b32_sdwa v85, v17, v13 dst_sel:DWORD dst_unused:UNUSED_PAD src0_sel:WORD_1 src1_sel:DWORD
	v_and_b32_sdwa v83, v15, v13 dst_sel:DWORD dst_unused:UNUSED_PAD src0_sel:WORD_1 src1_sel:DWORD
	v_and_b32_sdwa v84, v16, v13 dst_sel:DWORD dst_unused:UNUSED_PAD src0_sel:WORD_1 src1_sel:DWORD
	v_and_b32_sdwa v82, v14, v13 dst_sel:DWORD dst_unused:UNUSED_PAD src0_sel:WORD_1 src1_sel:DWORD
	v_add3_u32 v85, v17, v85, s13
	v_add3_u32 v83, v15, v83, s13
	v_add3_u32 v82, v14, v82, s13
	v_add3_u32 v84, v16, v84, s13
	v_and_b32_e32 v85, 0xffff0000, v85
	v_and_b32_e32 v83, 0xffff0000, v83
	v_or_b32_sdwa v87, v85, v84 dst_sel:DWORD dst_unused:UNUSED_PAD src0_sel:DWORD src1_sel:WORD_1
	v_or_b32_sdwa v86, v83, v82 dst_sel:DWORD dst_unused:UNUSED_PAD src0_sel:DWORD src1_sel:WORD_1
	global_store_dwordx2 v[64:65], v[86:87], off
	v_mul_f32_e32 v95, v15, v15
	v_fmac_f32_e32 v95, v14, v14
	v_fmac_f32_e32 v95, v16, v16
	v_fmac_f32_e32 v95, v17, v17
	s_waitcnt vmcnt(21)
	v_and_b32_sdwa v85, v21, v13 dst_sel:DWORD dst_unused:UNUSED_PAD src0_sel:WORD_1 src1_sel:DWORD
	v_and_b32_sdwa v83, v19, v13 dst_sel:DWORD dst_unused:UNUSED_PAD src0_sel:WORD_1 src1_sel:DWORD
	v_and_b32_sdwa v84, v20, v13 dst_sel:DWORD dst_unused:UNUSED_PAD src0_sel:WORD_1 src1_sel:DWORD
	v_and_b32_sdwa v82, v18, v13 dst_sel:DWORD dst_unused:UNUSED_PAD src0_sel:WORD_1 src1_sel:DWORD
	v_add3_u32 v85, v21, v85, s13
	v_add3_u32 v83, v19, v83, s13
	v_add3_u32 v82, v18, v82, s13
	v_add3_u32 v84, v20, v84, s13
	v_and_b32_e32 v85, 0xffff0000, v85
	v_and_b32_e32 v83, 0xffff0000, v83
	v_or_b32_sdwa v89, v85, v84 dst_sel:DWORD dst_unused:UNUSED_PAD src0_sel:DWORD src1_sel:WORD_1
	v_or_b32_sdwa v88, v83, v82 dst_sel:DWORD dst_unused:UNUSED_PAD src0_sel:DWORD src1_sel:WORD_1
	global_store_dwordx2 v[64:65], v[88:89], off offset:512
	v_mul_f32_e32 v94, v19, v19
	v_fmac_f32_e32 v94, v18, v18
	v_fmac_f32_e32 v94, v20, v20
	v_fmac_f32_e32 v94, v21, v21
	v_add_f32_e32 v95, v95, v94
	s_waitcnt vmcnt(21)
	v_and_b32_sdwa v85, v25, v13 dst_sel:DWORD dst_unused:UNUSED_PAD src0_sel:WORD_1 src1_sel:DWORD
	v_and_b32_sdwa v83, v23, v13 dst_sel:DWORD dst_unused:UNUSED_PAD src0_sel:WORD_1 src1_sel:DWORD
	v_and_b32_sdwa v84, v24, v13 dst_sel:DWORD dst_unused:UNUSED_PAD src0_sel:WORD_1 src1_sel:DWORD
	v_and_b32_sdwa v82, v22, v13 dst_sel:DWORD dst_unused:UNUSED_PAD src0_sel:WORD_1 src1_sel:DWORD
	v_add3_u32 v85, v25, v85, s13
	v_add3_u32 v83, v23, v83, s13
	v_add3_u32 v82, v22, v82, s13
	v_add3_u32 v84, v24, v84, s13
	v_and_b32_e32 v85, 0xffff0000, v85
	v_and_b32_e32 v83, 0xffff0000, v83
	v_or_b32_sdwa v91, v85, v84 dst_sel:DWORD dst_unused:UNUSED_PAD src0_sel:DWORD src1_sel:WORD_1
	v_or_b32_sdwa v90, v83, v82 dst_sel:DWORD dst_unused:UNUSED_PAD src0_sel:DWORD src1_sel:WORD_1
	global_store_dwordx2 v[64:65], v[90:91], off offset:1024
	v_mul_f32_e32 v94, v23, v23
	v_fmac_f32_e32 v94, v22, v22
	v_fmac_f32_e32 v94, v24, v24
	v_fmac_f32_e32 v94, v25, v25
	v_add_f32_e32 v95, v95, v94
	s_waitcnt vmcnt(21)
	v_and_b32_sdwa v85, v29, v13 dst_sel:DWORD dst_unused:UNUSED_PAD src0_sel:WORD_1 src1_sel:DWORD
	v_and_b32_sdwa v83, v27, v13 dst_sel:DWORD dst_unused:UNUSED_PAD src0_sel:WORD_1 src1_sel:DWORD
	v_and_b32_sdwa v84, v28, v13 dst_sel:DWORD dst_unused:UNUSED_PAD src0_sel:WORD_1 src1_sel:DWORD
	v_and_b32_sdwa v82, v26, v13 dst_sel:DWORD dst_unused:UNUSED_PAD src0_sel:WORD_1 src1_sel:DWORD
	v_add3_u32 v85, v29, v85, s13
	v_add3_u32 v83, v27, v83, s13
	v_add3_u32 v82, v26, v82, s13
	v_add3_u32 v84, v28, v84, s13
	v_and_b32_e32 v85, 0xffff0000, v85
	v_and_b32_e32 v83, 0xffff0000, v83
	v_or_b32_sdwa v93, v85, v84 dst_sel:DWORD dst_unused:UNUSED_PAD src0_sel:DWORD src1_sel:WORD_1
	v_or_b32_sdwa v92, v83, v82 dst_sel:DWORD dst_unused:UNUSED_PAD src0_sel:DWORD src1_sel:WORD_1
	global_store_dwordx2 v[64:65], v[92:93], off offset:1536
	v_mul_f32_e32 v94, v27, v27
	v_fmac_f32_e32 v94, v26, v26
	v_fmac_f32_e32 v94, v28, v28
	v_fmac_f32_e32 v94, v29, v29
	v_add_f32_e32 v95, v95, v94
	ds_bpermute_b32 v94, v6, v95
	s_waitcnt lgkmcnt(0)
	v_add_f32_e32 v95, v95, v94
	ds_bpermute_b32 v94, v7, v95
	s_waitcnt lgkmcnt(0)
	v_add_f32_e32 v95, v95, v94
	ds_bpermute_b32 v94, v8, v95
	s_waitcnt lgkmcnt(0)
	v_add_f32_e32 v95, v95, v94
	ds_bpermute_b32 v94, v9, v95
	s_waitcnt lgkmcnt(0)
	v_add_f32_e32 v95, v95, v94
	ds_bpermute_b32 v94, v10, v95
	s_waitcnt lgkmcnt(0)
	v_add_f32_e32 v95, v95, v94
	ds_bpermute_b32 v94, v11, v95
	s_waitcnt lgkmcnt(0)
	v_add_f32_e32 v95, v95, v94
	v_cmp_eq_u32_e32 vcc, 0, v4
	s_and_saveexec_b64 s[8:9], vcc
	v_fmamk_f32 v95, v95, 0x3a800000, v12
	v_mul_f32_e32 v94, 0x4b800000, v95
	v_cmp_gt_f32_e32 vcc, s14, v95
	v_lshl_add_u64 v[82:83], v[66:67], 2, s[4:5]
	s_nop 0
	v_cndmask_b32_e32 v95, v95, v94, vcc
	v_rsq_f32_e32 v95, v95
	s_nop 0
	v_mul_f32_e32 v94, 0x45800000, v95
	v_cndmask_b32_e32 v95, v95, v94, vcc
	global_store_dword v[82:83], v95, off
	s_or_b64 exec, exec, s[8:9]
	s_add_i32 s15, s15, s12
	s_cmpk_lt_i32 s15, 0x2000
	s_cbranch_scc0 .Lrn_exit
	s_mul_i32 s3, s12, 2
	s_add_i32 s3, s3, s15
	s_min_u32 s3, s3, 0x1fff
	s_lshl_b32 s3, s3, 2
	v_add_u32_e32 v66, s3, v5
	v_lshl_add_u32 v2, v66, 12, v80
	v_lshl_add_u64 v[62:63], s[16:17], 0, v[2:3]
	v_lshl_add_u32 v2, v66, 11, v81
	v_lshl_add_u64 v[64:65], s[0:1], 0, v[2:3]
	global_load_dwordx4 v[14:17], v[62:63], off
	global_load_dwordx4 v[18:21], v[62:63], off offset:1024
	global_load_dwordx4 v[22:25], v[62:63], off offset:2048
	global_load_dwordx4 v[26:29], v[62:63], off offset:3072
	s_waitcnt vmcnt(21)
	v_and_b32_sdwa v85, v33, v13 dst_sel:DWORD dst_unused:UNUSED_PAD src0_sel:WORD_1 src1_sel:DWORD
	v_and_b32_sdwa v83, v31, v13 dst_sel:DWORD dst_unused:UNUSED_PAD src0_sel:WORD_1 src1_sel:DWORD
	v_and_b32_sdwa v84, v32, v13 dst_sel:DWORD dst_unused:UNUSED_PAD src0_sel:WORD_1 src1_sel:DWORD
	v_and_b32_sdwa v82, v30, v13 dst_sel:DWORD dst_unused:UNUSED_PAD src0_sel:WORD_1 src1_sel:DWORD
	v_add3_u32 v85, v33, v85, s13
	v_add3_u32 v83, v31, v83, s13
	v_add3_u32 v82, v30, v82, s13
	v_add3_u32 v84, v32, v84, s13
	v_and_b32_e32 v85, 0xffff0000, v85
	v_and_b32_e32 v83, 0xffff0000, v83
	v_or_b32_sdwa v87, v85, v84 dst_sel:DWORD dst_unused:UNUSED_PAD src0_sel:DWORD src1_sel:WORD_1
	v_or_b32_sdwa v86, v83, v82 dst_sel:DWORD dst_unused:UNUSED_PAD src0_sel:DWORD src1_sel:WORD_1
	global_store_dwordx2 v[70:71], v[86:87], off
	v_mul_f32_e32 v95, v31, v31
	v_fmac_f32_e32 v95, v30, v30
	v_fmac_f32_e32 v95, v32, v32
	v_fmac_f32_e32 v95, v33, v33
	s_waitcnt vmcnt(21)
	v_and_b32_sdwa v85, v37, v13 dst_sel:DWORD dst_unused:UNUSED_PAD src0_sel:WORD_1 src1_sel:DWORD
	v_and_b32_sdwa v83, v35, v13 dst_sel:DWORD dst_unused:UNUSED_PAD src0_sel:WORD_1 src1_sel:DWORD
	v_and_b32_sdwa v84, v36, v13 dst_sel:DWORD dst_unused:UNUSED_PAD src0_sel:WORD_1 src1_sel:DWORD
	v_and_b32_sdwa v82, v34, v13 dst_sel:DWORD dst_unused:UNUSED_PAD src0_sel:WORD_1 src1_sel:DWORD
	v_add3_u32 v85, v37, v85, s13
	v_add3_u32 v83, v35, v83, s13
	v_add3_u32 v82, v34, v82, s13
	v_add3_u32 v84, v36, v84, s13
	v_and_b32_e32 v85, 0xffff0000, v85
	v_and_b32_e32 v83, 0xffff0000, v83
	v_or_b32_sdwa v89, v85, v84 dst_sel:DWORD dst_unused:UNUSED_PAD src0_sel:DWORD src1_sel:WORD_1
	v_or_b32_sdwa v88, v83, v82 dst_sel:DWORD dst_unused:UNUSED_PAD src0_sel:DWORD src1_sel:WORD_1
	global_store_dwordx2 v[70:71], v[88:89], off offset:512
	v_mul_f32_e32 v94, v35, v35
	v_fmac_f32_e32 v94, v34, v34
	v_fmac_f32_e32 v94, v36, v36
	v_fmac_f32_e32 v94, v37, v37
	v_add_f32_e32 v95, v95, v94
	s_waitcnt vmcnt(21)
	v_and_b32_sdwa v85, v41, v13 dst_sel:DWORD dst_unused:UNUSED_PAD src0_sel:WORD_1 src1_sel:DWORD
	v_and_b32_sdwa v83, v39, v13 dst_sel:DWORD dst_unused:UNUSED_PAD src0_sel:WORD_1 src1_sel:DWORD
	v_and_b32_sdwa v84, v40, v13 dst_sel:DWORD dst_unused:UNUSED_PAD src0_sel:WORD_1 src1_sel:DWORD
	v_and_b32_sdwa v82, v38, v13 dst_sel:DWORD dst_unused:UNUSED_PAD src0_sel:WORD_1 src1_sel:DWORD
	v_add3_u32 v85, v41, v85, s13
	v_add3_u32 v83, v39, v83, s13
	v_add3_u32 v82, v38, v82, s13
	v_add3_u32 v84, v40, v84, s13
	v_and_b32_e32 v85, 0xffff0000, v85
	v_and_b32_e32 v83, 0xffff0000, v83
	v_or_b32_sdwa v91, v85, v84 dst_sel:DWORD dst_unused:UNUSED_PAD src0_sel:DWORD src1_sel:WORD_1
	v_or_b32_sdwa v90, v83, v82 dst_sel:DWORD dst_unused:UNUSED_PAD src0_sel:DWORD src1_sel:WORD_1
	global_store_dwordx2 v[70:71], v[90:91], off offset:1024
	v_mul_f32_e32 v94, v39, v39
	v_fmac_f32_e32 v94, v38, v38
	v_fmac_f32_e32 v94, v40, v40
	v_fmac_f32_e32 v94, v41, v41
	v_add_f32_e32 v95, v95, v94
	s_waitcnt vmcnt(21)
	v_and_b32_sdwa v85, v45, v13 dst_sel:DWORD dst_unused:UNUSED_PAD src0_sel:WORD_1 src1_sel:DWORD
	v_and_b32_sdwa v83, v43, v13 dst_sel:DWORD dst_unused:UNUSED_PAD src0_sel:WORD_1 src1_sel:DWORD
	v_and_b32_sdwa v84, v44, v13 dst_sel:DWORD dst_unused:UNUSED_PAD src0_sel:WORD_1 src1_sel:DWORD
	v_and_b32_sdwa v82, v42, v13 dst_sel:DWORD dst_unused:UNUSED_PAD src0_sel:WORD_1 src1_sel:DWORD
	v_add3_u32 v85, v45, v85, s13
	v_add3_u32 v83, v43, v83, s13
	v_add3_u32 v82, v42, v82, s13
	v_add3_u32 v84, v44, v84, s13
	v_and_b32_e32 v85, 0xffff0000, v85
	v_and_b32_e32 v83, 0xffff0000, v83
	v_or_b32_sdwa v93, v85, v84 dst_sel:DWORD dst_unused:UNUSED_PAD src0_sel:DWORD src1_sel:WORD_1
	v_or_b32_sdwa v92, v83, v82 dst_sel:DWORD dst_unused:UNUSED_PAD src0_sel:DWORD src1_sel:WORD_1
	global_store_dwordx2 v[70:71], v[92:93], off offset:1536
	v_mul_f32_e32 v94, v43, v43
	v_fmac_f32_e32 v94, v42, v42
	v_fmac_f32_e32 v94, v44, v44
	v_fmac_f32_e32 v94, v45, v45
	v_add_f32_e32 v95, v95, v94
	ds_bpermute_b32 v94, v6, v95
	s_waitcnt lgkmcnt(0)
	v_add_f32_e32 v95, v95, v94
	ds_bpermute_b32 v94, v7, v95
	s_waitcnt lgkmcnt(0)
	v_add_f32_e32 v95, v95, v94
	ds_bpermute_b32 v94, v8, v95
	s_waitcnt lgkmcnt(0)
	v_add_f32_e32 v95, v95, v94
	ds_bpermute_b32 v94, v9, v95
	s_waitcnt lgkmcnt(0)
	v_add_f32_e32 v95, v95, v94
	ds_bpermute_b32 v94, v10, v95
	s_waitcnt lgkmcnt(0)
	v_add_f32_e32 v95, v95, v94
	ds_bpermute_b32 v94, v11, v95
	s_waitcnt lgkmcnt(0)
	v_add_f32_e32 v95, v95, v94
	v_cmp_eq_u32_e32 vcc, 0, v4
	s_and_saveexec_b64 s[8:9], vcc
	v_fmamk_f32 v95, v95, 0x3a800000, v12
	v_mul_f32_e32 v94, 0x4b800000, v95
	v_cmp_gt_f32_e32 vcc, s14, v95
	v_lshl_add_u64 v[82:83], v[72:73], 2, s[4:5]
	s_nop 0
	v_cndmask_b32_e32 v95, v95, v94, vcc
	v_rsq_f32_e32 v95, v95
	s_nop 0
	v_mul_f32_e32 v94, 0x45800000, v95
	v_cndmask_b32_e32 v95, v95, v94, vcc
	global_store_dword v[82:83], v95, off
	s_or_b64 exec, exec, s[8:9]
	s_add_i32 s15, s15, s12
	s_cmpk_lt_i32 s15, 0x2000
	s_cbranch_scc0 .Lrn_exit
	s_mul_i32 s3, s12, 2
	s_add_i32 s3, s3, s15
	s_min_u32 s3, s3, 0x1fff
	s_lshl_b32 s3, s3, 2
	v_add_u32_e32 v72, s3, v5
	v_lshl_add_u32 v2, v72, 12, v80
	v_lshl_add_u64 v[68:69], s[16:17], 0, v[2:3]
	v_lshl_add_u32 v2, v72, 11, v81
	v_lshl_add_u64 v[70:71], s[0:1], 0, v[2:3]
	global_load_dwordx4 v[30:33], v[68:69], off
	global_load_dwordx4 v[34:37], v[68:69], off offset:1024
	global_load_dwordx4 v[38:41], v[68:69], off offset:2048
	global_load_dwordx4 v[42:45], v[68:69], off offset:3072
	s_waitcnt vmcnt(21)
	v_and_b32_sdwa v85, v49, v13 dst_sel:DWORD dst_unused:UNUSED_PAD src0_sel:WORD_1 src1_sel:DWORD
	v_and_b32_sdwa v83, v47, v13 dst_sel:DWORD dst_unused:UNUSED_PAD src0_sel:WORD_1 src1_sel:DWORD
	v_and_b32_sdwa v84, v48, v13 dst_sel:DWORD dst_unused:UNUSED_PAD src0_sel:WORD_1 src1_sel:DWORD
	v_and_b32_sdwa v82, v46, v13 dst_sel:DWORD dst_unused:UNUSED_PAD src0_sel:WORD_1 src1_sel:DWORD
	v_add3_u32 v85, v49, v85, s13
	v_add3_u32 v83, v47, v83, s13
	v_add3_u32 v82, v46, v82, s13
	v_add3_u32 v84, v48, v84, s13
	v_and_b32_e32 v85, 0xffff0000, v85
	v_and_b32_e32 v83, 0xffff0000, v83
	v_or_b32_sdwa v87, v85, v84 dst_sel:DWORD dst_unused:UNUSED_PAD src0_sel:DWORD src1_sel:WORD_1
	v_or_b32_sdwa v86, v83, v82 dst_sel:DWORD dst_unused:UNUSED_PAD src0_sel:DWORD src1_sel:WORD_1
	global_store_dwordx2 v[76:77], v[86:87], off
	v_mul_f32_e32 v95, v47, v47
	v_fmac_f32_e32 v95, v46, v46
	v_fmac_f32_e32 v95, v48, v48
	v_fmac_f32_e32 v95, v49, v49
	s_waitcnt vmcnt(21)
	v_and_b32_sdwa v85, v53, v13 dst_sel:DWORD dst_unused:UNUSED_PAD src0_sel:WORD_1 src1_sel:DWORD
	v_and_b32_sdwa v83, v51, v13 dst_sel:DWORD dst_unused:UNUSED_PAD src0_sel:WORD_1 src1_sel:DWORD
	v_and_b32_sdwa v84, v52, v13 dst_sel:DWORD dst_unused:UNUSED_PAD src0_sel:WORD_1 src1_sel:DWORD
	v_and_b32_sdwa v82, v50, v13 dst_sel:DWORD dst_unused:UNUSED_PAD src0_sel:WORD_1 src1_sel:DWORD
	v_add3_u32 v85, v53, v85, s13
	v_add3_u32 v83, v51, v83, s13
	v_add3_u32 v82, v50, v82, s13
	v_add3_u32 v84, v52, v84, s13
	v_and_b32_e32 v85, 0xffff0000, v85
	v_and_b32_e32 v83, 0xffff0000, v83
	v_or_b32_sdwa v89, v85, v84 dst_sel:DWORD dst_unused:UNUSED_PAD src0_sel:DWORD src1_sel:WORD_1
	v_or_b32_sdwa v88, v83, v82 dst_sel:DWORD dst_unused:UNUSED_PAD src0_sel:DWORD src1_sel:WORD_1
	global_store_dwordx2 v[76:77], v[88:89], off offset:512
	v_mul_f32_e32 v94, v51, v51
	v_fmac_f32_e32 v94, v50, v50
	v_fmac_f32_e32 v94, v52, v52
	v_fmac_f32_e32 v94, v53, v53
	v_add_f32_e32 v95, v95, v94
	s_waitcnt vmcnt(21)
	v_and_b32_sdwa v85, v57, v13 dst_sel:DWORD dst_unused:UNUSED_PAD src0_sel:WORD_1 src1_sel:DWORD
	v_and_b32_sdwa v83, v55, v13 dst_sel:DWORD dst_unused:UNUSED_PAD src0_sel:WORD_1 src1_sel:DWORD
	v_and_b32_sdwa v84, v56, v13 dst_sel:DWORD dst_unused:UNUSED_PAD src0_sel:WORD_1 src1_sel:DWORD
	v_and_b32_sdwa v82, v54, v13 dst_sel:DWORD dst_unused:UNUSED_PAD src0_sel:WORD_1 src1_sel:DWORD
	v_add3_u32 v85, v57, v85, s13
	v_add3_u32 v83, v55, v83, s13
	v_add3_u32 v82, v54, v82, s13
	v_add3_u32 v84, v56, v84, s13
	v_and_b32_e32 v85, 0xffff0000, v85
	v_and_b32_e32 v83, 0xffff0000, v83
	v_or_b32_sdwa v91, v85, v84 dst_sel:DWORD dst_unused:UNUSED_PAD src0_sel:DWORD src1_sel:WORD_1
	v_or_b32_sdwa v90, v83, v82 dst_sel:DWORD dst_unused:UNUSED_PAD src0_sel:DWORD src1_sel:WORD_1
	global_store_dwordx2 v[76:77], v[90:91], off offset:1024
	v_mul_f32_e32 v94, v55, v55
	v_fmac_f32_e32 v94, v54, v54
	v_fmac_f32_e32 v94, v56, v56
	v_fmac_f32_e32 v94, v57, v57
	v_add_f32_e32 v95, v95, v94
	s_waitcnt vmcnt(21)
	v_and_b32_sdwa v85, v61, v13 dst_sel:DWORD dst_unused:UNUSED_PAD src0_sel:WORD_1 src1_sel:DWORD
	v_and_b32_sdwa v83, v59, v13 dst_sel:DWORD dst_unused:UNUSED_PAD src0_sel:WORD_1 src1_sel:DWORD
	v_and_b32_sdwa v84, v60, v13 dst_sel:DWORD dst_unused:UNUSED_PAD src0_sel:WORD_1 src1_sel:DWORD
	v_and_b32_sdwa v82, v58, v13 dst_sel:DWORD dst_unused:UNUSED_PAD src0_sel:WORD_1 src1_sel:DWORD
	v_add3_u32 v85, v61, v85, s13
	v_add3_u32 v83, v59, v83, s13
	v_add3_u32 v82, v58, v82, s13
	v_add3_u32 v84, v60, v84, s13
	v_and_b32_e32 v85, 0xffff0000, v85
	v_and_b32_e32 v83, 0xffff0000, v83
	v_or_b32_sdwa v93, v85, v84 dst_sel:DWORD dst_unused:UNUSED_PAD src0_sel:DWORD src1_sel:WORD_1
	v_or_b32_sdwa v92, v83, v82 dst_sel:DWORD dst_unused:UNUSED_PAD src0_sel:DWORD src1_sel:WORD_1
	global_store_dwordx2 v[76:77], v[92:93], off offset:1536
	v_mul_f32_e32 v94, v59, v59
	v_fmac_f32_e32 v94, v58, v58
	v_fmac_f32_e32 v94, v60, v60
	v_fmac_f32_e32 v94, v61, v61
	v_add_f32_e32 v95, v95, v94
	ds_bpermute_b32 v94, v6, v95
	s_waitcnt lgkmcnt(0)
	v_add_f32_e32 v95, v95, v94
	ds_bpermute_b32 v94, v7, v95
	s_waitcnt lgkmcnt(0)
	v_add_f32_e32 v95, v95, v94
	ds_bpermute_b32 v94, v8, v95
	s_waitcnt lgkmcnt(0)
	v_add_f32_e32 v95, v95, v94
	ds_bpermute_b32 v94, v9, v95
	s_waitcnt lgkmcnt(0)
	v_add_f32_e32 v95, v95, v94
	ds_bpermute_b32 v94, v10, v95
	s_waitcnt lgkmcnt(0)
	v_add_f32_e32 v95, v95, v94
	ds_bpermute_b32 v94, v11, v95
	s_waitcnt lgkmcnt(0)
	v_add_f32_e32 v95, v95, v94
	v_cmp_eq_u32_e32 vcc, 0, v4
	s_and_saveexec_b64 s[8:9], vcc
	v_fmamk_f32 v95, v95, 0x3a800000, v12
	v_mul_f32_e32 v94, 0x4b800000, v95
	v_cmp_gt_f32_e32 vcc, s14, v95
	v_lshl_add_u64 v[82:83], v[78:79], 2, s[4:5]
	s_nop 0
	v_cndmask_b32_e32 v95, v95, v94, vcc
	v_rsq_f32_e32 v95, v95
	s_nop 0
	v_mul_f32_e32 v94, 0x45800000, v95
	v_cndmask_b32_e32 v95, v95, v94, vcc
	global_store_dword v[82:83], v95, off
	s_or_b64 exec, exec, s[8:9]
	s_add_i32 s15, s15, s12
	s_cmpk_lt_i32 s15, 0x2000
	s_cbranch_scc1 .Lrn_loop
.Lrn_exit:
	v_readlane_b32 s18, v254, 8
	v_readlane_b32 s19, v254, 9
	v_readlane_b32 s20, v254, 10
	v_readlane_b32 s21, v254, 11
	v_readlane_b32 s22, v254, 12
	v_readlane_b32 s23, v254, 13
	v_readlane_b32 s24, v254, 14
	v_readlane_b32 s25, v254, 15
	v_readlane_b32 s26, v254, 16
	v_readlane_b32 s27, v254, 17
	v_readlane_b32 s28, v254, 18
	v_readlane_b32 s29, v254, 19
	v_readlane_b32 s30, v254, 20
	v_readlane_b32 s31, v254, 21
